# drop buffer_wbl2 at the 7 grid-barrier sites whose preceding phase now stores only write-through (sc1); kept after prologue and mixer-in
# speedup vs baseline: 1.0324x; 1.0060x over previous
.LBB0_312:
	s_andn2_saveexec_b64 s[10:11], s[10:11]
	s_cbranch_execz .LBB0_332
	s_mov_b64 s[10:11], exec
	s_waitcnt lgkmcnt(0)
	s_waitcnt vmcnt(0)
	v_mbcnt_lo_u32_b32 v1, s10, 0
	v_mbcnt_hi_u32_b32 v1, s11, v1
	v_cmp_eq_u32_e32 vcc, 0, v1
	s_and_saveexec_b64 s[12:13], vcc
	s_cbranch_execz .LBB0_315
	s_bcnt1_i32_b64 s2, s[10:11]
	v_mov_b32_e32 v2, s2
	v_mov_b32_e32 v3, 0x7000
	global_atomic_add v2, v3, v2, s[4:5] offset:1024 sc0

.LBB0_417:
	s_andn2_saveexec_b64 s[10:11], s[10:11]
	s_cbranch_execz .LBB0_437
	s_mov_b64 s[12:13], exec
	s_waitcnt lgkmcnt(0)
	s_waitcnt vmcnt(0)
	v_mbcnt_lo_u32_b32 v1, s12, 0
	v_mbcnt_hi_u32_b32 v1, s13, v1
	v_cmp_eq_u32_e32 vcc, 0, v1
	s_and_saveexec_b64 s[14:15], vcc
	s_cbranch_execz .LBB0_420
	s_bcnt1_i32_b64 s12, s[12:13]
	v_mov_b32_e32 v2, s12
	v_mov_b32_e32 v3, 0x7000
	global_atomic_add v2, v3, v2, s[4:5] offset:1024 sc0

.LBB0_498:
	s_andn2_saveexec_b64 s[12:13], s[12:13]
	s_cbranch_execz .LBB0_518
	s_mov_b64 s[14:15], exec
	s_waitcnt lgkmcnt(0)
	s_waitcnt vmcnt(0)
	v_mbcnt_lo_u32_b32 v1, s14, 0
	v_mbcnt_hi_u32_b32 v1, s15, v1
	v_cmp_eq_u32_e32 vcc, 0, v1
	s_and_saveexec_b64 s[16:17], vcc
	s_cbranch_execz .LBB0_501
	s_bcnt1_i32_b64 s2, s[14:15]
	v_mov_b32_e32 v2, s2
	v_mov_b32_e32 v3, 0x7000
	global_atomic_add v2, v3, v2, s[6:7] offset:1024 sc0

.LBB0_555:
	s_andn2_saveexec_b64 s[10:11], s[10:11]
	s_cbranch_execz .LBB0_575
	s_mov_b64 s[10:11], exec
	s_waitcnt lgkmcnt(0)
	s_waitcnt vmcnt(0)
	v_mbcnt_lo_u32_b32 v1, s10, 0
	v_mbcnt_hi_u32_b32 v1, s11, v1
	v_cmp_eq_u32_e32 vcc, 0, v1
	s_and_saveexec_b64 s[12:13], vcc
	s_cbranch_execz .LBB0_558
	s_bcnt1_i32_b64 s2, s[10:11]
	v_mov_b32_e32 v2, s2
	v_mov_b32_e32 v3, 0x7000
	global_atomic_add v2, v3, v2, s[6:7] offset:1024 sc0

.LBB0_1125:
	s_andn2_saveexec_b64 s[12:13], s[12:13]
	s_cbranch_execz .LBB0_1145
	s_mov_b64 s[12:13], exec
	s_waitcnt lgkmcnt(0)
	s_waitcnt vmcnt(0)
	v_mbcnt_lo_u32_b32 v1, s12, 0
	v_mbcnt_hi_u32_b32 v1, s13, v1
	v_cmp_eq_u32_e32 vcc, 0, v1
	s_and_saveexec_b64 s[14:15], vcc
	s_cbranch_execz .LBB0_1128
	s_bcnt1_i32_b64 s2, s[12:13]
	v_mov_b32_e32 v2, s2
	v_mov_b32_e32 v3, 0x7000
	global_atomic_add v2, v3, v2, s[6:7] offset:1024 sc0
